# removed all s_setprio flips from the three GEMM K-loops (equal priority for the MFMA and the loading wave of each SIMD)
# speedup vs baseline: 1.0073x; 1.0065x over previous
; #define PG8_STAGE(bufoff, gbase, voff) do { _Pragma("unroll") for (int _i = 0; _i < 2; ++_i) \
;         __builtin_amdgcn_global_load_lds((const unsigned*)((const char*)(gbase) + (voff)[_i]), (PG8_LAS unsigned*)(lds + (bufoff) + ldsw + _i * 8192), 16, 0, 0); } while (0)
; #define PG8_LDA(dst, b, h) do { _Pragma("unroll") for (int m = 0; m < 4; ++m) _Pragma("unroll") for (int k = 0; k < 2; ++k) dst[m][k] = *(const PG8_LAS bf16x8*)(lds + PG8_SA(b, h) + aoff + m * 2048 + k * 1024); } while (0)
; #define PG8_LDB(dst, b, h) do { _Pragma("unroll") for (int n = 0; n < 2; ++n) _Pragma("unroll") for (int k = 0; k < 2; ++k) dst[n][k] = *(const PG8_LAS bf16x8*)(lds + PG8_SB(b, h) + boff + n * 2048 + k * 1024); } while (0)
; #define PG8_MMA(ai, bj, At, Bt) do { __builtin_amdgcn_s_setprio(1); _Pragma("unroll") for (int m = 0; m < 4; ++m) _Pragma("unroll") for (int n = 0; n < 2; ++n) _Pragma("unroll") for (int k = 0; k < 2; ++k) \
;         acc[ai][bj][m][n] = __builtin_amdgcn_mfma_f32_16x16x32_bf16(Bt[n][k], At[m][k], acc[ai][bj][m][n], 0, 0, 0); __builtin_amdgcn_s_setprio(0); } while (0)
; #define PG8_WAIT_V(n) asm volatile("s_waitcnt vmcnt(" #n ")" ::: "memory")
; #define PG8_WAIT_L(n) asm volatile("s_waitcnt lgkmcnt(" #n ")" ::: "memory")
; #define PG8_BAR __builtin_amdgcn_s_barrier()
; #define PG8_SCHED __builtin_amdgcn_sched_barrier(0)
; template <class Epi, class Sched, bool ALIGN_EPI = false, bool SP2 = false>
; __device__ __forceinline__ void gemm_phase(PG8_LAS unsigned char* lds, const Gemm g, const Sched& S, const Epi& E, const int tid) {
;     ...
;             PG8_LDB(B0, 0, 0); PG8_LDB(B1, 0, 1); PG8_SCHED; PG8_LDA(At, 0, 0); PG8_STAGE(PG8_SA(1, 1), a1 + hstep, voffA);
;             PG8_WAIT_V(8); PG8_WAIT_L(0); PG8_BAR; PG8_MMA(0, 0, At, B0); PG8_MMA(0, 1, At, B1); PG8_BAR; PG8_SCHED;
;             PG8_LDA(At, 0, 1); PG8_STAGE(PG8_SB(0, 0), b2, voffB); PG8_STAGE(PG8_SB(0, 1), b2 + hstep, voffB); PG8_STAGE(PG8_SA(0, 0), a2, voffA);
.LBB0_150:
	s_add_u32 s10, s2, 0xfffc0080
	s_addc_u32 s11, s3, -1
	s_add_i32 s20, 0, 0x10000
	s_cmp_eq_u32 s17, 12
	s_cselect_b32 s13, s1, s11
	s_cselect_b32 s12, s6, s10
	s_cselect_b32 s11, s7, s16
	s_cselect_b32 s10, s14, s15
	s_add_i32 s53, 0, 0x14000
	v_add_u32_e32 v140, s20, v162
	v_add_u32_e32 v164, s53, v162
	ds_read_b128 v[128:131], v140
	ds_read_b128 v[132:135], v140 offset:1024
	ds_read_b128 v[136:139], v140 offset:2048
	ds_read_b128 v[140:143], v140 offset:3072
	ds_read_b128 v[156:159], v164
	ds_read_b128 v[180:183], v164 offset:1024
	ds_read_b128 v[184:187], v164 offset:2048
	ds_read_b128 v[188:191], v164 offset:3072
	v_lshl_add_u64 v[166:167], s[2:3], 0, v[154:155]
	s_add_i32 m0, s51, 0xc000
	ds_read_b128 v[192:195], v163
	ds_read_b128 v[196:199], v163 offset:1024
	ds_read_b128 v[214:217], v163 offset:2048
	ds_read_b128 v[218:221], v163 offset:3072
	ds_read_b128 v[222:225], v163 offset:4096
	ds_read_b128 v[226:229], v163 offset:5120
	ds_read_b128 v[230:233], v163 offset:6144
	ds_read_b128 v[234:237], v163 offset:7168
	global_load_lds_dwordx4 v[166:167], off
	v_lshl_add_u64 v[166:167], s[2:3], 0, v[152:153]
	s_add_i32 m0, s51, 0xe000
	s_nop 0
	global_load_lds_dwordx4 v[166:167], off
	s_waitcnt vmcnt(8)
	s_waitcnt lgkmcnt(0)
	s_barrier
	s_waitcnt lgkmcnt(0)
	v_mfma_f32_16x16x32_bf16 v[120:123], v[128:131], v[192:195], v[120:123]
	v_mfma_f32_16x16x32_bf16 v[124:127], v[136:139], v[192:195], v[124:127]
	v_mfma_f32_16x16x32_bf16 v[112:115], v[128:131], v[214:217], v[112:115]
	v_mfma_f32_16x16x32_bf16 v[116:119], v[136:139], v[214:217], v[116:119]
	v_mfma_f32_16x16x32_bf16 v[104:107], v[128:131], v[222:225], v[104:107]
	v_mfma_f32_16x16x32_bf16 v[108:111], v[136:139], v[222:225], v[108:111]
	v_mfma_f32_16x16x32_bf16 v[96:99], v[128:131], v[230:233], v[96:99]
	v_mfma_f32_16x16x32_bf16 v[100:103], v[136:139], v[230:233], v[100:103]
	v_mfma_f32_16x16x32_bf16 v[120:123], v[132:135], v[196:199], v[120:123]
	v_mfma_f32_16x16x32_bf16 v[124:127], v[140:143], v[196:199], v[124:127]
	v_mfma_f32_16x16x32_bf16 v[112:115], v[132:135], v[218:221], v[112:115]
	v_mfma_f32_16x16x32_bf16 v[116:119], v[140:143], v[218:221], v[116:119]
	v_mfma_f32_16x16x32_bf16 v[104:107], v[132:135], v[226:229], v[104:107]
	v_mfma_f32_16x16x32_bf16 v[108:111], v[140:143], v[226:229], v[108:111]
	v_mfma_f32_16x16x32_bf16 v[96:99], v[132:135], v[234:237], v[96:99]
	v_mfma_f32_16x16x32_bf16 v[100:103], v[140:143], v[234:237], v[100:103]
	v_mfma_f32_16x16x32_bf16 v[56:59], v[156:159], v[192:195], v[56:59]
	v_mfma_f32_16x16x32_bf16 v[60:63], v[184:187], v[192:195], v[60:63]
	v_mfma_f32_16x16x32_bf16 v[48:51], v[156:159], v[214:217], v[48:51]
	v_mfma_f32_16x16x32_bf16 v[52:55], v[184:187], v[214:217], v[52:55]
	v_mfma_f32_16x16x32_bf16 v[40:43], v[156:159], v[222:225], v[40:43]
	v_mfma_f32_16x16x32_bf16 v[44:47], v[184:187], v[222:225], v[44:47]
	v_mfma_f32_16x16x32_bf16 v[32:35], v[156:159], v[230:233], v[32:35]
	v_mfma_f32_16x16x32_bf16 v[36:39], v[184:187], v[230:233], v[36:39]
	v_mfma_f32_16x16x32_bf16 v[56:59], v[180:183], v[196:199], v[56:59]
	v_mfma_f32_16x16x32_bf16 v[60:63], v[188:191], v[196:199], v[60:63]
	v_mfma_f32_16x16x32_bf16 v[48:51], v[180:183], v[218:221], v[48:51]
	v_mfma_f32_16x16x32_bf16 v[52:55], v[188:191], v[218:221], v[52:55]
	v_mfma_f32_16x16x32_bf16 v[40:43], v[180:183], v[226:229], v[40:43]
	v_mfma_f32_16x16x32_bf16 v[44:47], v[188:191], v[226:229], v[44:47]
	v_mfma_f32_16x16x32_bf16 v[32:35], v[180:183], v[234:237], v[32:35]
	v_mfma_f32_16x16x32_bf16 v[36:39], v[188:191], v[234:237], v[36:39]
	s_barrier
	s_add_i32 s20, s20, s50
	v_lshl_add_u64 v[166:167], s[10:11], 0, v[146:147]
	s_mov_b32 m0, s20
	ds_read_b128 v[192:195], v163 offset:16384
	ds_read_b128 v[196:199], v163 offset:17408
	ds_read_b128 v[214:217], v163 offset:18432
	ds_read_b128 v[218:221], v163 offset:19456
	ds_read_b128 v[222:225], v163 offset:20480
	ds_read_b128 v[226:229], v163 offset:21504
	ds_read_b128 v[230:233], v163 offset:22528
	ds_read_b128 v[234:237], v163 offset:23552
	global_load_lds_dwordx4 v[166:167], off
	s_add_i32 m0, s20, 0x2000
	s_add_u32 s20, s10, 0x40000
	v_lshl_add_u64 v[200:201], s[10:11], 0, v[150:151]
	s_addc_u32 s21, s11, 0
	s_add_i32 s53, s53, s50
	global_load_lds_dwordx4 v[200:201], off
	v_lshl_add_u64 v[238:239], s[20:21], 0, v[146:147]
	s_mov_b32 m0, s53
	v_lshl_add_u64 v[240:241], s[12:13], 0, v[148:149]
	global_load_lds_dwordx4 v[238:239], off
	v_lshl_add_u64 v[238:239], s[20:21], 0, v[150:151]
	s_add_i32 m0, s53, 0x2000
	s_nop 0
	global_load_lds_dwordx4 v[238:239], off
	v_lshl_add_u64 v[238:239], s[12:13], 0, v[144:145]
	s_mov_b32 m0, s51
	s_nop 0
	global_load_lds_dwordx4 v[238:239], off
	s_mov_b32 m0, s55
	s_nop 0
	global_load_lds_dwordx4 v[240:241], off
	s_waitcnt vmcnt(8)
	s_waitcnt lgkmcnt(0)
	s_barrier
; #define PG8_STAGE(bufoff, gbase, voff) do { _Pragma("unroll") for (int _i = 0; _i < 2; ++_i) \
;         __builtin_amdgcn_global_load_lds((const unsigned*)((const char*)(gbase) + (voff)[_i]), (PG8_LAS unsigned*)(lds + (bufoff) + ldsw + _i * 8192), 16, 0, 0); } while (0)
; #define PG8_LDA(dst, b, h) do { _Pragma("unroll") for (int m = 0; m < 4; ++m) _Pragma("unroll") for (int k = 0; k < 2; ++k) dst[m][k] = *(const PG8_LAS bf16x8*)(lds + PG8_SA(b, h) + aoff + m * 2048 + k * 1024); } while (0)
; #define PG8_LDB(dst, b, h) do { _Pragma("unroll") for (int n = 0; n < 2; ++n) _Pragma("unroll") for (int k = 0; k < 2; ++k) dst[n][k] = *(const PG8_LAS bf16x8*)(lds + PG8_SB(b, h) + boff + n * 2048 + k * 1024); } while (0)
; #define PG8_MMA(ai, bj, At, Bt) do { __builtin_amdgcn_s_setprio(1); _Pragma("unroll") for (int m = 0; m < 4; ++m) _Pragma("unroll") for (int n = 0; n < 2; ++n) _Pragma("unroll") for (int k = 0; k < 2; ++k) \
;         acc[ai][bj][m][n] = __builtin_amdgcn_mfma_f32_16x16x32_bf16(Bt[n][k], At[m][k], acc[ai][bj][m][n], 0, 0, 0); __builtin_amdgcn_s_setprio(0); } while (0)
; #define PG8_WAIT_V(n) asm volatile("s_waitcnt vmcnt(" #n ")" ::: "memory")
; #define PG8_WAIT_L(n) asm volatile("s_waitcnt lgkmcnt(" #n ")" ::: "memory")
; #define PG8_BAR __builtin_amdgcn_s_barrier()
; #define PG8_SCHED __builtin_amdgcn_sched_barrier(0)
; template <class Epi, class Sched, bool ALIGN_EPI = false, bool SP2 = false>
; __device__ __forceinline__ void gemm_phase(PG8_LAS unsigned char* lds, const Gemm g, const Sched& S, const Epi& E, const int tid) {
;     ...
;             PG8_WAIT_V(8); PG8_WAIT_L(0); PG8_BAR; PG8_MMA(1, 0, At, B0); PG8_MMA(1, 1, At, B1); PG8_BAR; PG8_SCHED;
;             PG8_LDB(B0, 1, 0); PG8_LDB(B1, 1, 1); PG8_SCHED; PG8_LDA(At, 1, 0); PG8_STAGE(PG8_SA(0, 1), a2 + hstep, voffA);
;             PG8_WAIT_V(8); PG8_WAIT_L(0); PG8_BAR; PG8_MMA(0, 0, At, B0); PG8_MMA(0, 1, At, B1); PG8_BAR; PG8_SCHED;
	s_waitcnt lgkmcnt(0)
	v_mfma_f32_16x16x32_bf16 v[88:91], v[128:131], v[192:195], v[88:91]
	v_mfma_f32_16x16x32_bf16 v[92:95], v[136:139], v[192:195], v[92:95]
	v_mfma_f32_16x16x32_bf16 v[80:83], v[128:131], v[214:217], v[80:83]
	v_mfma_f32_16x16x32_bf16 v[84:87], v[136:139], v[214:217], v[84:87]
	v_mfma_f32_16x16x32_bf16 v[72:75], v[128:131], v[222:225], v[72:75]
	v_mfma_f32_16x16x32_bf16 v[76:79], v[136:139], v[222:225], v[76:79]
	v_mfma_f32_16x16x32_bf16 v[64:67], v[128:131], v[230:233], v[64:67]
	v_mfma_f32_16x16x32_bf16 v[68:71], v[136:139], v[230:233], v[68:71]
	v_mfma_f32_16x16x32_bf16 v[88:91], v[132:135], v[196:199], v[88:91]
	v_mfma_f32_16x16x32_bf16 v[92:95], v[140:143], v[196:199], v[92:95]
	v_mfma_f32_16x16x32_bf16 v[80:83], v[132:135], v[218:221], v[80:83]
	v_mfma_f32_16x16x32_bf16 v[84:87], v[140:143], v[218:221], v[84:87]
	v_mfma_f32_16x16x32_bf16 v[72:75], v[132:135], v[226:229], v[72:75]
	v_mfma_f32_16x16x32_bf16 v[76:79], v[140:143], v[226:229], v[76:79]
	v_mfma_f32_16x16x32_bf16 v[64:67], v[132:135], v[234:237], v[64:67]
	v_mfma_f32_16x16x32_bf16 v[68:71], v[140:143], v[234:237], v[68:71]
	v_mfma_f32_16x16x32_bf16 v[24:27], v[156:159], v[192:195], v[24:27]
	v_mfma_f32_16x16x32_bf16 v[28:31], v[184:187], v[192:195], v[28:31]
	v_mfma_f32_16x16x32_bf16 v[16:19], v[156:159], v[214:217], v[16:19]
	v_mfma_f32_16x16x32_bf16 v[20:23], v[184:187], v[214:217], v[20:23]
	v_mfma_f32_16x16x32_bf16 v[8:11], v[156:159], v[222:225], v[8:11]
	v_mfma_f32_16x16x32_bf16 v[12:15], v[184:187], v[222:225], v[12:15]
	v_mfma_f32_16x16x32_bf16 v[4:7], v[156:159], v[230:233], v[4:7]
	v_mfma_f32_16x16x32_bf16 v[0:3], v[184:187], v[230:233], v[0:3]
	v_mfma_f32_16x16x32_bf16 v[24:27], v[180:183], v[196:199], v[24:27]
	v_mfma_f32_16x16x32_bf16 v[28:31], v[188:191], v[196:199], v[28:31]
	v_mfma_f32_16x16x32_bf16 v[16:19], v[180:183], v[218:221], v[16:19]
	v_mfma_f32_16x16x32_bf16 v[20:23], v[188:191], v[218:221], v[20:23]
	v_mfma_f32_16x16x32_bf16 v[8:11], v[180:183], v[226:229], v[8:11]
	v_mfma_f32_16x16x32_bf16 v[12:15], v[188:191], v[226:229], v[12:15]
	v_mfma_f32_16x16x32_bf16 v[4:7], v[180:183], v[234:237], v[4:7]
	v_mfma_f32_16x16x32_bf16 v[0:3], v[188:191], v[234:237], v[0:3]
	s_barrier
	s_add_i32 s20, 0, 0x18000
	s_add_i32 s21, 0, 0x1c000
	v_add_u32_e32 v140, s20, v162
	v_add_u32_e32 v164, s21, v162
	ds_read_b128 v[128:131], v140
	ds_read_b128 v[132:135], v140 offset:1024
	ds_read_b128 v[136:139], v140 offset:2048
	ds_read_b128 v[140:143], v140 offset:3072
	ds_read_b128 v[156:159], v164
	ds_read_b128 v[180:183], v164 offset:1024
	ds_read_b128 v[184:187], v164 offset:2048
	ds_read_b128 v[188:191], v164 offset:3072
	s_add_u32 s12, s12, 0x40000
	s_addc_u32 s13, s13, 0
	s_mov_b32 m0, s81
	v_lshl_add_u64 v[242:243], s[12:13], 0, v[144:145]
	ds_read_b128 v[192:195], v163 offset:32768
	ds_read_b128 v[196:199], v163 offset:33792
	ds_read_b128 v[214:217], v163 offset:34816
	ds_read_b128 v[218:221], v163 offset:35840
	ds_read_b128 v[222:225], v163 offset:36864
	ds_read_b128 v[226:229], v163 offset:37888
	ds_read_b128 v[230:233], v163 offset:38912
	ds_read_b128 v[234:237], v163 offset:39936
	global_load_lds_dwordx4 v[242:243], off
	v_lshl_add_u64 v[242:243], s[12:13], 0, v[148:149]
	s_mov_b32 m0, s38
	s_nop 0
	global_load_lds_dwordx4 v[242:243], off
	s_waitcnt vmcnt(8)
	s_waitcnt lgkmcnt(0)
	s_barrier
	s_waitcnt lgkmcnt(0)
	v_mfma_f32_16x16x32_bf16 v[120:123], v[128:131], v[192:195], v[120:123]
	v_mfma_f32_16x16x32_bf16 v[124:127], v[136:139], v[192:195], v[124:127]
	v_mfma_f32_16x16x32_bf16 v[112:115], v[128:131], v[214:217], v[112:115]
	v_mfma_f32_16x16x32_bf16 v[116:119], v[136:139], v[214:217], v[116:119]
	v_mfma_f32_16x16x32_bf16 v[104:107], v[128:131], v[222:225], v[104:107]
	v_mfma_f32_16x16x32_bf16 v[108:111], v[136:139], v[222:225], v[108:111]
	v_mfma_f32_16x16x32_bf16 v[96:99], v[128:131], v[230:233], v[96:99]
	v_mfma_f32_16x16x32_bf16 v[100:103], v[136:139], v[230:233], v[100:103]
	v_mfma_f32_16x16x32_bf16 v[120:123], v[132:135], v[196:199], v[120:123]
	v_mfma_f32_16x16x32_bf16 v[124:127], v[140:143], v[196:199], v[124:127]
	v_mfma_f32_16x16x32_bf16 v[112:115], v[132:135], v[218:221], v[112:115]
	v_mfma_f32_16x16x32_bf16 v[116:119], v[140:143], v[218:221], v[116:119]
	v_mfma_f32_16x16x32_bf16 v[104:107], v[132:135], v[226:229], v[104:107]
	v_mfma_f32_16x16x32_bf16 v[108:111], v[140:143], v[226:229], v[108:111]
	v_mfma_f32_16x16x32_bf16 v[96:99], v[132:135], v[234:237], v[96:99]
	v_mfma_f32_16x16x32_bf16 v[100:103], v[140:143], v[234:237], v[100:103]
	v_mfma_f32_16x16x32_bf16 v[56:59], v[156:159], v[192:195], v[56:59]
	v_mfma_f32_16x16x32_bf16 v[60:63], v[184:187], v[192:195], v[60:63]
	v_mfma_f32_16x16x32_bf16 v[48:51], v[156:159], v[214:217], v[48:51]
	v_mfma_f32_16x16x32_bf16 v[52:55], v[184:187], v[214:217], v[52:55]
	v_mfma_f32_16x16x32_bf16 v[40:43], v[156:159], v[222:225], v[40:43]
	v_mfma_f32_16x16x32_bf16 v[44:47], v[184:187], v[222:225], v[44:47]
	v_mfma_f32_16x16x32_bf16 v[32:35], v[156:159], v[230:233], v[32:35]
	v_mfma_f32_16x16x32_bf16 v[36:39], v[184:187], v[230:233], v[36:39]
	v_mfma_f32_16x16x32_bf16 v[56:59], v[180:183], v[196:199], v[56:59]
	v_mfma_f32_16x16x32_bf16 v[60:63], v[188:191], v[196:199], v[60:63]
	v_mfma_f32_16x16x32_bf16 v[48:51], v[180:183], v[218:221], v[48:51]
	v_mfma_f32_16x16x32_bf16 v[52:55], v[188:191], v[218:221], v[52:55]
	v_mfma_f32_16x16x32_bf16 v[40:43], v[180:183], v[226:229], v[40:43]
	v_mfma_f32_16x16x32_bf16 v[44:47], v[188:191], v[226:229], v[44:47]
	v_mfma_f32_16x16x32_bf16 v[32:35], v[180:183], v[234:237], v[32:35]
	v_mfma_f32_16x16x32_bf16 v[36:39], v[188:191], v[234:237], v[36:39]
	s_barrier
; #define PG8_STAGE(bufoff, gbase, voff) do { _Pragma("unroll") for (int _i = 0; _i < 2; ++_i) \
;         __builtin_amdgcn_global_load_lds((const unsigned*)((const char*)(gbase) + (voff)[_i]), (PG8_LAS unsigned*)(lds + (bufoff) + ldsw + _i * 8192), 16, 0, 0); } while (0)
; #define PG8_LDA(dst, b, h) do { _Pragma("unroll") for (int m = 0; m < 4; ++m) _Pragma("unroll") for (int k = 0; k < 2; ++k) dst[m][k] = *(const PG8_LAS bf16x8*)(lds + PG8_SA(b, h) + aoff + m * 2048 + k * 1024); } while (0)
; #define PG8_MMA(ai, bj, At, Bt) do { __builtin_amdgcn_s_setprio(1); _Pragma("unroll") for (int m = 0; m < 4; ++m) _Pragma("unroll") for (int n = 0; n < 2; ++n) _Pragma("unroll") for (int k = 0; k < 2; ++k) \
;         acc[ai][bj][m][n] = __builtin_amdgcn_mfma_f32_16x16x32_bf16(Bt[n][k], At[m][k], acc[ai][bj][m][n], 0, 0, 0); __builtin_amdgcn_s_setprio(0); } while (0)
; #define PG8_WAIT_V(n) asm volatile("s_waitcnt vmcnt(" #n ")" ::: "memory")
; #define PG8_WAIT_L(n) asm volatile("s_waitcnt lgkmcnt(" #n ")" ::: "memory")
; #define PG8_BAR __builtin_amdgcn_s_barrier()
; #define PG8_SCHED __builtin_amdgcn_sched_barrier(0)
; template <class Epi, class Sched, bool ALIGN_EPI = false, bool SP2 = false>
; __device__ __forceinline__ void gemm_phase(PG8_LAS unsigned char* lds, const Gemm g, const Sched& S, const Epi& E, const int tid) {
;     ...
;             PG8_LDA(At, 1, 1); PG8_STAGE(PG8_SB(1, 0), b3, voffB); PG8_STAGE(PG8_SB(1, 1), b3 + hstep, voffB); PG8_STAGE(PG8_SA(1, 0), a3, voffA);
;             PG8_WAIT_V(8); PG8_WAIT_L(0); PG8_BAR; PG8_MMA(1, 0, At, B0); PG8_MMA(1, 1, At, B1); PG8_BAR; PG8_SCHED;
	s_add_i32 s12, s20, s50
	v_lshl_add_u64 v[166:167], v[166:167], 0, s[86:87]
	s_mov_b32 m0, s12
	ds_read_b128 v[192:195], v163 offset:49152
	ds_read_b128 v[196:199], v163 offset:50176
	ds_read_b128 v[214:217], v163 offset:51200
	ds_read_b128 v[218:221], v163 offset:52224
	ds_read_b128 v[222:225], v163 offset:53248
	ds_read_b128 v[226:229], v163 offset:54272
	ds_read_b128 v[230:233], v163 offset:55296
	ds_read_b128 v[234:237], v163 offset:56320
	global_load_lds_dwordx4 v[166:167], off
	s_add_i32 m0, s12, 0x2000
	s_add_u32 s10, s10, 0x40080
	v_lshl_add_u64 v[166:167], v[200:201], 0, s[86:87]
	s_addc_u32 s11, s11, 0
	s_add_i32 s12, s21, s50
	global_load_lds_dwordx4 v[166:167], off
	v_lshl_add_u64 v[166:167], s[10:11], 0, v[146:147]
	s_mov_b32 m0, s12
	s_nop 0
	global_load_lds_dwordx4 v[166:167], off
	v_lshl_add_u64 v[166:167], s[10:11], 0, v[150:151]
	s_add_i32 m0, s12, 0x2000
	s_nop 0
	global_load_lds_dwordx4 v[166:167], off
	v_lshl_add_u64 v[166:167], v[238:239], 0, s[86:87]
	s_mov_b32 m0, s37
	s_nop 0
	global_load_lds_dwordx4 v[166:167], off
	v_lshl_add_u64 v[166:167], v[240:241], 0, s[86:87]
	s_mov_b32 m0, s41
	s_nop 0
	global_load_lds_dwordx4 v[166:167], off
	s_waitcnt vmcnt(8)
	s_waitcnt lgkmcnt(0)
	s_barrier
	s_waitcnt lgkmcnt(0)
	v_mfma_f32_16x16x32_bf16 v[88:91], v[128:131], v[192:195], v[88:91]
	v_mfma_f32_16x16x32_bf16 v[92:95], v[136:139], v[192:195], v[92:95]
	v_mfma_f32_16x16x32_bf16 v[80:83], v[128:131], v[214:217], v[80:83]
	v_mfma_f32_16x16x32_bf16 v[84:87], v[136:139], v[214:217], v[84:87]
	v_mfma_f32_16x16x32_bf16 v[72:75], v[128:131], v[222:225], v[72:75]
	v_mfma_f32_16x16x32_bf16 v[76:79], v[136:139], v[222:225], v[76:79]
	v_mfma_f32_16x16x32_bf16 v[64:67], v[128:131], v[230:233], v[64:67]
	v_mfma_f32_16x16x32_bf16 v[68:71], v[136:139], v[230:233], v[68:71]
	v_mfma_f32_16x16x32_bf16 v[88:91], v[132:135], v[196:199], v[88:91]
	v_mfma_f32_16x16x32_bf16 v[92:95], v[140:143], v[196:199], v[92:95]
	v_mfma_f32_16x16x32_bf16 v[80:83], v[132:135], v[218:221], v[80:83]
	v_mfma_f32_16x16x32_bf16 v[84:87], v[140:143], v[218:221], v[84:87]
	v_mfma_f32_16x16x32_bf16 v[72:75], v[132:135], v[226:229], v[72:75]
	v_mfma_f32_16x16x32_bf16 v[76:79], v[140:143], v[226:229], v[76:79]
	v_mfma_f32_16x16x32_bf16 v[64:67], v[132:135], v[234:237], v[64:67]
	v_mfma_f32_16x16x32_bf16 v[68:71], v[140:143], v[234:237], v[68:71]
	v_mfma_f32_16x16x32_bf16 v[24:27], v[156:159], v[192:195], v[24:27]
	v_mfma_f32_16x16x32_bf16 v[28:31], v[184:187], v[192:195], v[28:31]
	v_mfma_f32_16x16x32_bf16 v[16:19], v[156:159], v[214:217], v[16:19]
	v_mfma_f32_16x16x32_bf16 v[20:23], v[184:187], v[214:217], v[20:23]
	v_mfma_f32_16x16x32_bf16 v[8:11], v[156:159], v[222:225], v[8:11]
	v_mfma_f32_16x16x32_bf16 v[12:15], v[184:187], v[222:225], v[12:15]
	v_mfma_f32_16x16x32_bf16 v[4:7], v[156:159], v[230:233], v[4:7]
	v_mfma_f32_16x16x32_bf16 v[0:3], v[184:187], v[230:233], v[0:3]
	v_mfma_f32_16x16x32_bf16 v[24:27], v[180:183], v[196:199], v[24:27]
	v_mfma_f32_16x16x32_bf16 v[28:31], v[188:191], v[196:199], v[28:31]
	v_mfma_f32_16x16x32_bf16 v[16:19], v[180:183], v[218:221], v[16:19]
	v_mfma_f32_16x16x32_bf16 v[20:23], v[188:191], v[218:221], v[20:23]
	v_mfma_f32_16x16x32_bf16 v[8:11], v[180:183], v[226:229], v[8:11]
	v_mfma_f32_16x16x32_bf16 v[12:15], v[188:191], v[226:229], v[12:15]
	v_mfma_f32_16x16x32_bf16 v[4:7], v[180:183], v[234:237], v[4:7]
	v_mfma_f32_16x16x32_bf16 v[0:3], v[188:191], v[234:237], v[0:3]
	s_barrier
	s_add_i32 s17, s17, 2
	s_add_u32 s15, s15, 0x100
	s_addc_u32 s16, s16, 0
	s_add_u32 s2, s2, 0x100
	s_addc_u32 s3, s3, 0
	s_cmp_gt_u32 s17, 13
	s_cbranch_scc0 .LBB0_150
	v_readlane_b32 s2, v255, 13
	v_readlane_b32 s3, v255, 14
	s_and_b64 vcc, exec, s[2:3]
	s_cbranch_vccz .LBB0_153
	s_barrier

; #define PG8_STAGE(bufoff, gbase, voff) do { _Pragma("unroll") for (int _i = 0; _i < 2; ++_i) \
;         __builtin_amdgcn_global_load_lds((const unsigned*)((const char*)(gbase) + (voff)[_i]), (PG8_LAS unsigned*)(lds + (bufoff) + ldsw + _i * 8192), 16, 0, 0); } while (0)
; #define PG8_LDA(dst, b, h) do { _Pragma("unroll") for (int m = 0; m < 4; ++m) _Pragma("unroll") for (int k = 0; k < 2; ++k) dst[m][k] = *(const PG8_LAS bf16x8*)(lds + PG8_SA(b, h) + aoff + m * 2048 + k * 1024); } while (0)
; #define PG8_LDB(dst, b, h) do { _Pragma("unroll") for (int n = 0; n < 2; ++n) _Pragma("unroll") for (int k = 0; k < 2; ++k) dst[n][k] = *(const PG8_LAS bf16x8*)(lds + PG8_SB(b, h) + boff + n * 2048 + k * 1024); } while (0)
; #define PG8_MMA(ai, bj, At, Bt) do { __builtin_amdgcn_s_setprio(1); _Pragma("unroll") for (int m = 0; m < 4; ++m) _Pragma("unroll") for (int n = 0; n < 2; ++n) _Pragma("unroll") for (int k = 0; k < 2; ++k) \
;         acc[ai][bj][m][n] = __builtin_amdgcn_mfma_f32_16x16x32_bf16(Bt[n][k], At[m][k], acc[ai][bj][m][n], 0, 0, 0); __builtin_amdgcn_s_setprio(0); } while (0)
; #define PG8_WAIT_V(n) asm volatile("s_waitcnt vmcnt(" #n ")" ::: "memory")
; #define PG8_WAIT_L(n) asm volatile("s_waitcnt lgkmcnt(" #n ")" ::: "memory")
; #define PG8_BAR __builtin_amdgcn_s_barrier()
; #define PG8_SCHED __builtin_amdgcn_sched_barrier(0)
; template <class Epi, class Sched, bool ALIGN_EPI = false, bool SP2 = false>
; __device__ __forceinline__ void gemm_phase(PG8_LAS unsigned char* lds, const Gemm g, const Sched& S, const Epi& E, const int tid) {
;     ...
;             PG8_LDB(B0, 0, 0); PG8_LDB(B1, 0, 1); PG8_SCHED; PG8_LDA(At, 0, 0); PG8_STAGE(PG8_SA(1, 1), a1 + hstep, voffA);
;             PG8_WAIT_V(8); PG8_WAIT_L(0); PG8_BAR; PG8_MMA(0, 0, At, B0); PG8_MMA(0, 1, At, B1); PG8_BAR; PG8_SCHED;
;             PG8_LDA(At, 0, 1); PG8_STAGE(PG8_SB(0, 0), b2, voffB); PG8_STAGE(PG8_SB(0, 1), b2 + hstep, voffB); PG8_STAGE(PG8_SA(0, 0), a2, voffA);
.LBB0_1305:
	s_add_i32 s84, s54, 2
	s_add_u32 s85, s8, 0x80
	s_addc_u32 s55, s9, 0
	s_add_i32 s82, 0, 0x10000
	s_cmp_eq_u32 s62, s54
	s_cselect_b32 s55, s1, s55
	s_cselect_b32 s54, s0, s85
	s_cselect_b32 vcc_hi, s21, s81
	s_cselect_b32 vcc_lo, s20, s73
	s_add_i32 s85, 0, 0x14000
	v_add_u32_e32 v52, s82, v181
	v_add_u32_e32 v156, s85, v181
	ds_read_b128 v[32:35], v52
	ds_read_b128 v[36:39], v52 offset:1024
	ds_read_b128 v[48:51], v52 offset:2048
	ds_read_b128 v[52:55], v52 offset:3072
	ds_read_b128 v[144:147], v156
	ds_read_b128 v[148:151], v156 offset:1024
	ds_read_b128 v[152:155], v156 offset:2048
	ds_read_b128 v[156:159], v156 offset:3072
	v_lshl_add_u64 v[200:201], s[8:9], 0, v[186:187]
	s_add_i32 m0, s45, 0xc000
	ds_read_b128 v[188:191], v218
	ds_read_b128 v[192:195], v218 offset:1024
	ds_read_b128 v[196:199], v218 offset:2048
	ds_read_b128 v[222:225], v218 offset:3072
	ds_read_b128 v[226:229], v218 offset:4096
	ds_read_b128 v[230:233], v218 offset:5120
	ds_read_b128 v[234:237], v218 offset:6144
	ds_read_b128 v[238:241], v218 offset:7168
	global_load_lds_dwordx4 v[200:201], off
	v_lshl_add_u64 v[200:201], s[8:9], 0, v[184:185]
	s_add_i32 m0, s45, 0xe000
	s_nop 0
	global_load_lds_dwordx4 v[200:201], off
	s_waitcnt vmcnt(8)
	s_waitcnt lgkmcnt(0)
	s_barrier
	s_waitcnt lgkmcnt(0)
	v_mfma_f32_16x16x32_bf16 v[140:143], v[32:35], v[188:191], v[140:143]
	v_mfma_f32_16x16x32_bf16 v[136:139], v[48:51], v[188:191], v[136:139]
	v_mfma_f32_16x16x32_bf16 v[124:127], v[32:35], v[196:199], v[124:127]
	v_mfma_f32_16x16x32_bf16 v[120:123], v[48:51], v[196:199], v[120:123]
	v_mfma_f32_16x16x32_bf16 v[108:111], v[32:35], v[226:229], v[108:111]
	v_mfma_f32_16x16x32_bf16 v[104:107], v[48:51], v[226:229], v[104:107]
	v_mfma_f32_16x16x32_bf16 v[92:95], v[32:35], v[234:237], v[92:95]
	v_mfma_f32_16x16x32_bf16 v[88:91], v[48:51], v[234:237], v[88:91]
	v_mfma_f32_16x16x32_bf16 v[140:143], v[36:39], v[192:195], v[140:143]
	v_mfma_f32_16x16x32_bf16 v[136:139], v[52:55], v[192:195], v[136:139]
	v_mfma_f32_16x16x32_bf16 v[124:127], v[36:39], v[222:225], v[124:127]
	v_mfma_f32_16x16x32_bf16 v[120:123], v[52:55], v[222:225], v[120:123]
	v_mfma_f32_16x16x32_bf16 v[108:111], v[36:39], v[230:233], v[108:111]
	v_mfma_f32_16x16x32_bf16 v[104:107], v[52:55], v[230:233], v[104:107]
	v_mfma_f32_16x16x32_bf16 v[92:95], v[36:39], v[238:241], v[92:95]
	v_mfma_f32_16x16x32_bf16 v[88:91], v[52:55], v[238:241], v[88:91]
	v_mfma_f32_16x16x32_bf16 v[132:135], v[144:147], v[188:191], v[132:135]
	v_mfma_f32_16x16x32_bf16 v[128:131], v[152:155], v[188:191], v[128:131]
	v_mfma_f32_16x16x32_bf16 v[116:119], v[144:147], v[196:199], v[116:119]
	v_mfma_f32_16x16x32_bf16 v[112:115], v[152:155], v[196:199], v[112:115]
	v_mfma_f32_16x16x32_bf16 v[100:103], v[144:147], v[226:229], v[100:103]
	v_mfma_f32_16x16x32_bf16 v[96:99], v[152:155], v[226:229], v[96:99]
	v_mfma_f32_16x16x32_bf16 v[84:87], v[144:147], v[234:237], v[84:87]
	v_mfma_f32_16x16x32_bf16 v[80:83], v[152:155], v[234:237], v[80:83]
	v_mfma_f32_16x16x32_bf16 v[132:135], v[148:151], v[192:195], v[132:135]
	v_mfma_f32_16x16x32_bf16 v[128:131], v[156:159], v[192:195], v[128:131]
	v_mfma_f32_16x16x32_bf16 v[116:119], v[148:151], v[222:225], v[116:119]
	v_mfma_f32_16x16x32_bf16 v[112:115], v[156:159], v[222:225], v[112:115]
	v_mfma_f32_16x16x32_bf16 v[100:103], v[148:151], v[230:233], v[100:103]
	v_mfma_f32_16x16x32_bf16 v[96:99], v[156:159], v[230:233], v[96:99]
	v_mfma_f32_16x16x32_bf16 v[84:87], v[148:151], v[238:241], v[84:87]
	v_mfma_f32_16x16x32_bf16 v[80:83], v[156:159], v[238:241], v[80:83]
	s_barrier
	s_add_i32 s82, s82, s38
	v_lshl_add_u64 v[200:201], vcc, 0, v[164:165]
	s_mov_b32 m0, s82
	ds_read_b128 v[188:191], v218 offset:16384
	ds_read_b128 v[192:195], v218 offset:17408
	ds_read_b128 v[196:199], v218 offset:18432
	ds_read_b128 v[222:225], v218 offset:19456
	ds_read_b128 v[226:229], v218 offset:20480
	ds_read_b128 v[230:233], v218 offset:21504
	ds_read_b128 v[234:237], v218 offset:22528
	ds_read_b128 v[238:241], v218 offset:23552
	global_load_lds_dwordx4 v[200:201], off
	s_add_i32 m0, s82, 0x2000
	v_lshl_add_u64 v[242:243], vcc, 0, v[160:161]
	s_add_u32 vcc_lo, vcc_lo, s90
	s_addc_u32 vcc_hi, vcc_hi, 0
	s_add_i32 s82, s85, s38
	global_load_lds_dwordx4 v[242:243], off
	v_lshl_add_u64 v[244:245], vcc, 0, v[164:165]
	s_mov_b32 m0, s82
	v_lshl_add_u64 v[246:247], vcc, 0, v[160:161]
	global_load_lds_dwordx4 v[244:245], off
	s_add_i32 m0, s82, 0x2000
	v_lshl_add_u64 v[248:249], s[54:55], 0, v[164:165]
	global_load_lds_dwordx4 v[246:247], off
	s_mov_b32 m0, s45
	v_lshl_add_u64 v[250:251], s[54:55], 0, v[160:161]
	global_load_lds_dwordx4 v[248:249], off
	s_mov_b32 m0, s48
	s_nop 0
	global_load_lds_dwordx4 v[250:251], off
	s_waitcnt vmcnt(8)
	s_waitcnt lgkmcnt(0)
	s_barrier
; #define PG8_STAGE(bufoff, gbase, voff) do { _Pragma("unroll") for (int _i = 0; _i < 2; ++_i) \
;         __builtin_amdgcn_global_load_lds((const unsigned*)((const char*)(gbase) + (voff)[_i]), (PG8_LAS unsigned*)(lds + (bufoff) + ldsw + _i * 8192), 16, 0, 0); } while (0)
; #define PG8_LDA(dst, b, h) do { _Pragma("unroll") for (int m = 0; m < 4; ++m) _Pragma("unroll") for (int k = 0; k < 2; ++k) dst[m][k] = *(const PG8_LAS bf16x8*)(lds + PG8_SA(b, h) + aoff + m * 2048 + k * 1024); } while (0)
; #define PG8_LDB(dst, b, h) do { _Pragma("unroll") for (int n = 0; n < 2; ++n) _Pragma("unroll") for (int k = 0; k < 2; ++k) dst[n][k] = *(const PG8_LAS bf16x8*)(lds + PG8_SB(b, h) + boff + n * 2048 + k * 1024); } while (0)
; #define PG8_MMA(ai, bj, At, Bt) do { __builtin_amdgcn_s_setprio(1); _Pragma("unroll") for (int m = 0; m < 4; ++m) _Pragma("unroll") for (int n = 0; n < 2; ++n) _Pragma("unroll") for (int k = 0; k < 2; ++k) \
;         acc[ai][bj][m][n] = __builtin_amdgcn_mfma_f32_16x16x32_bf16(Bt[n][k], At[m][k], acc[ai][bj][m][n], 0, 0, 0); __builtin_amdgcn_s_setprio(0); } while (0)
; #define PG8_WAIT_V(n) asm volatile("s_waitcnt vmcnt(" #n ")" ::: "memory")
; #define PG8_WAIT_L(n) asm volatile("s_waitcnt lgkmcnt(" #n ")" ::: "memory")
; #define PG8_BAR __builtin_amdgcn_s_barrier()
; #define PG8_SCHED __builtin_amdgcn_sched_barrier(0)
; template <class Epi, class Sched, bool ALIGN_EPI = false, bool SP2 = false>
; __device__ __forceinline__ void gemm_phase(PG8_LAS unsigned char* lds, const Gemm g, const Sched& S, const Epi& E, const int tid) {
;     ...
;             PG8_WAIT_V(8); PG8_WAIT_L(0); PG8_BAR; PG8_MMA(1, 0, At, B0); PG8_MMA(1, 1, At, B1); PG8_BAR; PG8_SCHED;
;             PG8_LDB(B0, 1, 0); PG8_LDB(B1, 1, 1); PG8_SCHED; PG8_LDA(At, 1, 0); PG8_STAGE(PG8_SA(0, 1), a2 + hstep, voffA);
;             PG8_WAIT_V(8); PG8_WAIT_L(0); PG8_BAR; PG8_MMA(0, 0, At, B0); PG8_MMA(0, 1, At, B1); PG8_BAR; PG8_SCHED;
	s_waitcnt lgkmcnt(0)
	v_mfma_f32_16x16x32_bf16 v[76:79], v[32:35], v[188:191], v[76:79]
	v_mfma_f32_16x16x32_bf16 v[72:75], v[48:51], v[188:191], v[72:75]
	v_mfma_f32_16x16x32_bf16 v[60:63], v[32:35], v[196:199], v[60:63]
	v_mfma_f32_16x16x32_bf16 v[56:59], v[48:51], v[196:199], v[56:59]
	v_mfma_f32_16x16x32_bf16 v[28:31], v[32:35], v[226:229], v[28:31]
	v_mfma_f32_16x16x32_bf16 v[24:27], v[48:51], v[226:229], v[24:27]
	v_mfma_f32_16x16x32_bf16 v[12:15], v[32:35], v[234:237], v[12:15]
	v_mfma_f32_16x16x32_bf16 v[8:11], v[48:51], v[234:237], v[8:11]
	v_mfma_f32_16x16x32_bf16 v[76:79], v[36:39], v[192:195], v[76:79]
	v_mfma_f32_16x16x32_bf16 v[72:75], v[52:55], v[192:195], v[72:75]
	v_mfma_f32_16x16x32_bf16 v[60:63], v[36:39], v[222:225], v[60:63]
	v_mfma_f32_16x16x32_bf16 v[56:59], v[52:55], v[222:225], v[56:59]
	v_mfma_f32_16x16x32_bf16 v[28:31], v[36:39], v[230:233], v[28:31]
	v_mfma_f32_16x16x32_bf16 v[24:27], v[52:55], v[230:233], v[24:27]
	v_mfma_f32_16x16x32_bf16 v[12:15], v[36:39], v[238:241], v[12:15]
	v_mfma_f32_16x16x32_bf16 v[8:11], v[52:55], v[238:241], v[8:11]
	v_mfma_f32_16x16x32_bf16 v[44:47], v[144:147], v[196:199], v[44:47]
	v_mfma_f32_16x16x32_bf16 v[40:43], v[152:155], v[196:199], v[40:43]
	v_mfma_f32_16x16x32_bf16 v[20:23], v[144:147], v[226:229], v[20:23]
	v_mfma_f32_16x16x32_bf16 v[16:19], v[152:155], v[226:229], v[16:19]
	v_mfma_f32_16x16x32_bf16 v[4:7], v[144:147], v[234:237], v[4:7]
	v_mfma_f32_16x16x32_bf16 v[0:3], v[152:155], v[234:237], v[0:3]
	v_mfma_f32_16x16x32_bf16 v[32:35], v[144:147], v[188:191], v[68:71]
	v_mfma_f32_16x16x32_bf16 v[36:39], v[152:155], v[188:191], v[64:67]
	v_mfma_f32_16x16x32_bf16 v[44:47], v[148:151], v[222:225], v[44:47]
	v_mfma_f32_16x16x32_bf16 v[40:43], v[156:159], v[222:225], v[40:43]
	v_mfma_f32_16x16x32_bf16 v[20:23], v[148:151], v[230:233], v[20:23]
	v_mfma_f32_16x16x32_bf16 v[16:19], v[156:159], v[230:233], v[16:19]
	v_mfma_f32_16x16x32_bf16 v[4:7], v[148:151], v[238:241], v[4:7]
	v_mfma_f32_16x16x32_bf16 v[0:3], v[156:159], v[238:241], v[0:3]
	v_mfma_f32_16x16x32_bf16 v[32:35], v[148:151], v[192:195], v[32:35]
	v_mfma_f32_16x16x32_bf16 v[36:39], v[156:159], v[192:195], v[36:39]
	s_barrier
	s_add_i32 s82, 0, 0x18000
	s_add_i32 s85, 0, 0x1c000
	v_add_u32_e32 v68, s82, v181
	v_add_u32_e32 v156, s85, v181
	ds_read_b128 v[48:51], v68
	ds_read_b128 v[52:55], v68 offset:1024
	ds_read_b128 v[64:67], v68 offset:2048
	ds_read_b128 v[68:71], v68 offset:3072
	ds_read_b128 v[144:147], v156
	ds_read_b128 v[148:151], v156 offset:1024
	ds_read_b128 v[152:155], v156 offset:2048
	ds_read_b128 v[156:159], v156 offset:3072
	s_add_u32 s54, s54, s90
	s_addc_u32 s55, s55, 0
	s_mov_b32 m0, s49
	v_lshl_add_u64 v[166:167], s[54:55], 0, v[164:165]
	ds_read_b128 v[188:191], v218 offset:32768
	ds_read_b128 v[192:195], v218 offset:33792
	ds_read_b128 v[196:199], v218 offset:34816
	ds_read_b128 v[222:225], v218 offset:35840
	ds_read_b128 v[226:229], v218 offset:36864
	ds_read_b128 v[230:233], v218 offset:37888
	ds_read_b128 v[234:237], v218 offset:38912
	ds_read_b128 v[238:241], v218 offset:39936
	global_load_lds_dwordx4 v[166:167], off
	v_lshl_add_u64 v[166:167], s[54:55], 0, v[160:161]
	s_mov_b32 m0, s50
	s_nop 0
	global_load_lds_dwordx4 v[166:167], off
	s_waitcnt vmcnt(8)
	s_waitcnt lgkmcnt(0)
	s_barrier
	s_waitcnt lgkmcnt(0)
	v_mfma_f32_16x16x32_bf16 v[140:143], v[48:51], v[188:191], v[140:143]
	v_mfma_f32_16x16x32_bf16 v[136:139], v[64:67], v[188:191], v[136:139]
	v_mfma_f32_16x16x32_bf16 v[124:127], v[48:51], v[196:199], v[124:127]
	v_mfma_f32_16x16x32_bf16 v[120:123], v[64:67], v[196:199], v[120:123]
	v_mfma_f32_16x16x32_bf16 v[108:111], v[48:51], v[226:229], v[108:111]
	v_mfma_f32_16x16x32_bf16 v[104:107], v[64:67], v[226:229], v[104:107]
	v_mfma_f32_16x16x32_bf16 v[92:95], v[48:51], v[234:237], v[92:95]
	v_mfma_f32_16x16x32_bf16 v[88:91], v[64:67], v[234:237], v[88:91]
	v_mfma_f32_16x16x32_bf16 v[140:143], v[52:55], v[192:195], v[140:143]
	v_mfma_f32_16x16x32_bf16 v[136:139], v[68:71], v[192:195], v[136:139]
	v_mfma_f32_16x16x32_bf16 v[124:127], v[52:55], v[222:225], v[124:127]
	v_mfma_f32_16x16x32_bf16 v[120:123], v[68:71], v[222:225], v[120:123]
	v_mfma_f32_16x16x32_bf16 v[108:111], v[52:55], v[230:233], v[108:111]
	v_mfma_f32_16x16x32_bf16 v[104:107], v[68:71], v[230:233], v[104:107]
	v_mfma_f32_16x16x32_bf16 v[92:95], v[52:55], v[238:241], v[92:95]
	v_mfma_f32_16x16x32_bf16 v[88:91], v[68:71], v[238:241], v[88:91]
	v_mfma_f32_16x16x32_bf16 v[132:135], v[144:147], v[188:191], v[132:135]
	v_mfma_f32_16x16x32_bf16 v[128:131], v[152:155], v[188:191], v[128:131]
	v_mfma_f32_16x16x32_bf16 v[116:119], v[144:147], v[196:199], v[116:119]
	v_mfma_f32_16x16x32_bf16 v[112:115], v[152:155], v[196:199], v[112:115]
	v_mfma_f32_16x16x32_bf16 v[100:103], v[144:147], v[226:229], v[100:103]
	v_mfma_f32_16x16x32_bf16 v[96:99], v[152:155], v[226:229], v[96:99]
	v_mfma_f32_16x16x32_bf16 v[84:87], v[144:147], v[234:237], v[84:87]
	v_mfma_f32_16x16x32_bf16 v[80:83], v[152:155], v[234:237], v[80:83]
	v_mfma_f32_16x16x32_bf16 v[132:135], v[148:151], v[192:195], v[132:135]
	v_mfma_f32_16x16x32_bf16 v[128:131], v[156:159], v[192:195], v[128:131]
	v_mfma_f32_16x16x32_bf16 v[116:119], v[148:151], v[222:225], v[116:119]
	v_mfma_f32_16x16x32_bf16 v[112:115], v[156:159], v[222:225], v[112:115]
	v_mfma_f32_16x16x32_bf16 v[100:103], v[148:151], v[230:233], v[100:103]
	v_mfma_f32_16x16x32_bf16 v[96:99], v[156:159], v[230:233], v[96:99]
	v_mfma_f32_16x16x32_bf16 v[84:87], v[148:151], v[238:241], v[84:87]
	v_mfma_f32_16x16x32_bf16 v[80:83], v[156:159], v[238:241], v[80:83]
	s_barrier
; #define PG8_STAGE(bufoff, gbase, voff) do { _Pragma("unroll") for (int _i = 0; _i < 2; ++_i) \
;         __builtin_amdgcn_global_load_lds((const unsigned*)((const char*)(gbase) + (voff)[_i]), (PG8_LAS unsigned*)(lds + (bufoff) + ldsw + _i * 8192), 16, 0, 0); } while (0)
; #define PG8_LDA(dst, b, h) do { _Pragma("unroll") for (int m = 0; m < 4; ++m) _Pragma("unroll") for (int k = 0; k < 2; ++k) dst[m][k] = *(const PG8_LAS bf16x8*)(lds + PG8_SA(b, h) + aoff + m * 2048 + k * 1024); } while (0)
; #define PG8_MMA(ai, bj, At, Bt) do { __builtin_amdgcn_s_setprio(1); _Pragma("unroll") for (int m = 0; m < 4; ++m) _Pragma("unroll") for (int n = 0; n < 2; ++n) _Pragma("unroll") for (int k = 0; k < 2; ++k) \
;         acc[ai][bj][m][n] = __builtin_amdgcn_mfma_f32_16x16x32_bf16(Bt[n][k], At[m][k], acc[ai][bj][m][n], 0, 0, 0); __builtin_amdgcn_s_setprio(0); } while (0)
; #define PG8_WAIT_V(n) asm volatile("s_waitcnt vmcnt(" #n ")" ::: "memory")
; #define PG8_WAIT_L(n) asm volatile("s_waitcnt lgkmcnt(" #n ")" ::: "memory")
; #define PG8_BAR __builtin_amdgcn_s_barrier()
; #define PG8_SCHED __builtin_amdgcn_sched_barrier(0)
; template <class Epi, class Sched, bool ALIGN_EPI = false, bool SP2 = false>
; __device__ __forceinline__ void gemm_phase(PG8_LAS unsigned char* lds, const Gemm g, const Sched& S, const Epi& E, const int tid) {
;     ...
;             PG8_LDA(At, 1, 1); PG8_STAGE(PG8_SB(1, 0), b3, voffB); PG8_STAGE(PG8_SB(1, 1), b3 + hstep, voffB); PG8_STAGE(PG8_SA(1, 0), a3, voffA);
;             PG8_WAIT_V(8); PG8_WAIT_L(0); PG8_BAR; PG8_MMA(1, 0, At, B0); PG8_MMA(1, 1, At, B1); PG8_BAR; PG8_SCHED;
	s_add_i32 s54, s82, s38
	v_lshl_add_u64 v[166:167], v[200:201], 0, s[86:87]
	s_mov_b32 m0, s54
	ds_read_b128 v[188:191], v218 offset:49152
	ds_read_b128 v[192:195], v218 offset:50176
	ds_read_b128 v[196:199], v218 offset:51200
	ds_read_b128 v[222:225], v218 offset:52224
	ds_read_b128 v[226:229], v218 offset:53248
	ds_read_b128 v[230:233], v218 offset:54272
	ds_read_b128 v[234:237], v218 offset:55296
	ds_read_b128 v[238:241], v218 offset:56320
	global_load_lds_dwordx4 v[166:167], off
	v_lshl_add_u64 v[166:167], v[242:243], 0, s[86:87]
	s_add_i32 m0, s54, 0x2000
	s_add_i32 s54, s85, s38
	global_load_lds_dwordx4 v[166:167], off
	v_lshl_add_u64 v[166:167], v[244:245], 0, s[86:87]
	s_mov_b32 m0, s54
	s_nop 0
	global_load_lds_dwordx4 v[166:167], off
	v_lshl_add_u64 v[166:167], v[246:247], 0, s[86:87]
	s_add_i32 m0, s54, 0x2000
	s_nop 0
	global_load_lds_dwordx4 v[166:167], off
	v_lshl_add_u64 v[166:167], v[248:249], 0, s[86:87]
	s_mov_b32 m0, s57
	s_nop 0
	global_load_lds_dwordx4 v[166:167], off
	v_lshl_add_u64 v[166:167], v[250:251], 0, s[86:87]
	s_mov_b32 m0, s58
	s_nop 0
	global_load_lds_dwordx4 v[166:167], off
	s_waitcnt vmcnt(8)
	s_waitcnt lgkmcnt(0)
	s_barrier
	s_waitcnt lgkmcnt(0)
	v_mfma_f32_16x16x32_bf16 v[76:79], v[48:51], v[188:191], v[76:79]
	v_mfma_f32_16x16x32_bf16 v[72:75], v[64:67], v[188:191], v[72:75]
	v_mfma_f32_16x16x32_bf16 v[60:63], v[48:51], v[196:199], v[60:63]
	v_mfma_f32_16x16x32_bf16 v[56:59], v[64:67], v[196:199], v[56:59]
	v_mfma_f32_16x16x32_bf16 v[28:31], v[48:51], v[226:229], v[28:31]
	v_mfma_f32_16x16x32_bf16 v[24:27], v[64:67], v[226:229], v[24:27]
	v_mfma_f32_16x16x32_bf16 v[12:15], v[48:51], v[234:237], v[12:15]
	v_mfma_f32_16x16x32_bf16 v[8:11], v[64:67], v[234:237], v[8:11]
	v_mfma_f32_16x16x32_bf16 v[76:79], v[52:55], v[192:195], v[76:79]
	v_mfma_f32_16x16x32_bf16 v[72:75], v[68:71], v[192:195], v[72:75]
	v_mfma_f32_16x16x32_bf16 v[60:63], v[52:55], v[222:225], v[60:63]
	v_mfma_f32_16x16x32_bf16 v[56:59], v[68:71], v[222:225], v[56:59]
	v_mfma_f32_16x16x32_bf16 v[28:31], v[52:55], v[230:233], v[28:31]
	v_mfma_f32_16x16x32_bf16 v[24:27], v[68:71], v[230:233], v[24:27]
	v_mfma_f32_16x16x32_bf16 v[12:15], v[52:55], v[238:241], v[12:15]
	v_mfma_f32_16x16x32_bf16 v[8:11], v[68:71], v[238:241], v[8:11]
	v_mfma_f32_16x16x32_bf16 v[32:35], v[144:147], v[188:191], v[32:35]
	v_mfma_f32_16x16x32_bf16 v[68:71], v[148:151], v[192:195], v[32:35]
	v_mfma_f32_16x16x32_bf16 v[32:35], v[152:155], v[188:191], v[36:39]
	v_mfma_f32_16x16x32_bf16 v[64:67], v[156:159], v[192:195], v[32:35]
	v_mfma_f32_16x16x32_bf16 v[32:35], v[144:147], v[196:199], v[44:47]
	v_mfma_f32_16x16x32_bf16 v[44:47], v[148:151], v[222:225], v[32:35]
	v_mfma_f32_16x16x32_bf16 v[32:35], v[152:155], v[196:199], v[40:43]
	v_mfma_f32_16x16x32_bf16 v[20:23], v[144:147], v[226:229], v[20:23]
	v_mfma_f32_16x16x32_bf16 v[16:19], v[152:155], v[226:229], v[16:19]
	v_mfma_f32_16x16x32_bf16 v[4:7], v[144:147], v[234:237], v[4:7]
	v_mfma_f32_16x16x32_bf16 v[0:3], v[152:155], v[234:237], v[0:3]
	v_mfma_f32_16x16x32_bf16 v[40:43], v[156:159], v[222:225], v[32:35]
	v_mfma_f32_16x16x32_bf16 v[20:23], v[148:151], v[230:233], v[20:23]
	v_mfma_f32_16x16x32_bf16 v[16:19], v[156:159], v[230:233], v[16:19]
	v_mfma_f32_16x16x32_bf16 v[4:7], v[148:151], v[238:241], v[4:7]
	v_mfma_f32_16x16x32_bf16 v[0:3], v[156:159], v[238:241], v[0:3]
	s_barrier
	s_add_u32 s73, s73, 0x100
	s_addc_u32 s81, s81, 0
	s_add_u32 s8, s8, 0x100
	s_addc_u32 s9, s9, 0
	s_cmp_ge_u32 s84, s60
	s_mov_b32 s54, s84
	s_cbranch_scc0 .LBB0_1305
	s_and_b64 vcc, exec, s[18:19]
	s_cbranch_vccz .LBB0_1308
	s_barrier

; #define PG8_STAGE(bufoff, gbase, voff) do { _Pragma("unroll") for (int _i = 0; _i < 2; ++_i) \
;         __builtin_amdgcn_global_load_lds((const unsigned*)((const char*)(gbase) + (voff)[_i]), (PG8_LAS unsigned*)(lds + (bufoff) + ldsw + _i * 8192), 16, 0, 0); } while (0)
; #define PG8_LDA(dst, b, h) do { _Pragma("unroll") for (int m = 0; m < 4; ++m) _Pragma("unroll") for (int k = 0; k < 2; ++k) dst[m][k] = *(const PG8_LAS bf16x8*)(lds + PG8_SA(b, h) + aoff + m * 2048 + k * 1024); } while (0)
; #define PG8_LDB(dst, b, h) do { _Pragma("unroll") for (int n = 0; n < 2; ++n) _Pragma("unroll") for (int k = 0; k < 2; ++k) dst[n][k] = *(const PG8_LAS bf16x8*)(lds + PG8_SB(b, h) + boff + n * 2048 + k * 1024); } while (0)
; #define PG8_MMA(ai, bj, At, Bt) do { __builtin_amdgcn_s_setprio(1); _Pragma("unroll") for (int m = 0; m < 4; ++m) _Pragma("unroll") for (int n = 0; n < 2; ++n) _Pragma("unroll") for (int k = 0; k < 2; ++k) \
;         acc[ai][bj][m][n] = __builtin_amdgcn_mfma_f32_16x16x32_bf16(Bt[n][k], At[m][k], acc[ai][bj][m][n], 0, 0, 0); __builtin_amdgcn_s_setprio(0); } while (0)
; #define PG8_WAIT_V(n) asm volatile("s_waitcnt vmcnt(" #n ")" ::: "memory")
; #define PG8_WAIT_L(n) asm volatile("s_waitcnt lgkmcnt(" #n ")" ::: "memory")
; #define PG8_BAR __builtin_amdgcn_s_barrier()
; #define PG8_SCHED __builtin_amdgcn_sched_barrier(0)
; template <class Epi, class Sched, bool ALIGN_EPI = false, bool SP2 = false>
; __device__ __forceinline__ void gemm_phase(PG8_LAS unsigned char* lds, const Gemm g, const Sched& S, const Epi& E, const int tid) {
;     ...
;             PG8_LDB(B0, 0, 0); PG8_LDB(B1, 0, 1); PG8_SCHED; PG8_LDA(At, 0, 0); PG8_STAGE(PG8_SA(1, 1), a1 + hstep, voffA);
;             PG8_WAIT_V(8); PG8_WAIT_L(0); PG8_BAR; PG8_MMA(0, 0, At, B0); PG8_MMA(0, 1, At, B1); PG8_BAR; PG8_SCHED;
;             PG8_LDA(At, 0, 1); PG8_STAGE(PG8_SB(0, 0), b2, voffB); PG8_STAGE(PG8_SB(0, 1), b2 + hstep, voffB); PG8_STAGE(PG8_SA(0, 0), a2, voffA);
.LBB0_1492:
	s_add_u32 s20, s18, 0xfffc0080
	s_addc_u32 s21, s19, -1
	s_add_i32 s60, 0, 0x10000
	s_cmp_eq_u32 s59, 12
	s_cselect_b32 s53, s11, s21
	s_cselect_b32 s52, s55, s20
	s_cselect_b32 s21, s9, s58
	s_cselect_b32 s20, s56, s57
	s_add_i32 s62, 0, 0x14000
	v_add_u32_e32 v154, s60, v143
	v_add_u32_e32 v162, s62, v143
	ds_read_b128 v[138:141], v154
	ds_read_b128 v[146:149], v154 offset:1024
	ds_read_b128 v[150:153], v154 offset:2048
	ds_read_b128 v[154:157], v154 offset:3072
	ds_read_b128 v[158:161], v162
	ds_read_b128 v[180:183], v162 offset:1024
	ds_read_b128 v[184:187], v162 offset:2048
	ds_read_b128 v[188:191], v162 offset:3072
	v_lshl_add_u64 v[162:163], s[18:19], 0, v[136:137]
	s_add_i32 m0, s43, 0xc000
	ds_read_b128 v[192:195], v145
	ds_read_b128 v[196:199], v145 offset:1024
	ds_read_b128 v[214:217], v145 offset:2048
	ds_read_b128 v[218:221], v145 offset:3072
	ds_read_b128 v[222:225], v145 offset:4096
	ds_read_b128 v[226:229], v145 offset:5120
	ds_read_b128 v[230:233], v145 offset:6144
	ds_read_b128 v[234:237], v145 offset:7168
	global_load_lds_dwordx4 v[162:163], off
	v_lshl_add_u64 v[162:163], s[18:19], 0, v[134:135]
	s_add_i32 m0, s43, 0xe000
	s_nop 0
	global_load_lds_dwordx4 v[162:163], off
	s_waitcnt vmcnt(8)
	s_waitcnt lgkmcnt(0)
	s_barrier
	s_waitcnt lgkmcnt(0)
	v_mfma_f32_16x16x32_bf16 v[124:127], v[138:141], v[192:195], v[124:127]
	v_mfma_f32_16x16x32_bf16 v[116:119], v[150:153], v[192:195], v[116:119]
	v_mfma_f32_16x16x32_bf16 v[108:111], v[138:141], v[214:217], v[108:111]
	v_mfma_f32_16x16x32_bf16 v[100:103], v[150:153], v[214:217], v[100:103]
	v_mfma_f32_16x16x32_bf16 v[92:95], v[138:141], v[222:225], v[92:95]
	v_mfma_f32_16x16x32_bf16 v[84:87], v[150:153], v[222:225], v[84:87]
	v_mfma_f32_16x16x32_bf16 v[76:79], v[138:141], v[230:233], v[76:79]
	v_mfma_f32_16x16x32_bf16 v[68:71], v[150:153], v[230:233], v[68:71]
	v_mfma_f32_16x16x32_bf16 v[124:127], v[146:149], v[196:199], v[124:127]
	v_mfma_f32_16x16x32_bf16 v[116:119], v[154:157], v[196:199], v[116:119]
	v_mfma_f32_16x16x32_bf16 v[108:111], v[146:149], v[218:221], v[108:111]
	v_mfma_f32_16x16x32_bf16 v[100:103], v[154:157], v[218:221], v[100:103]
	v_mfma_f32_16x16x32_bf16 v[92:95], v[146:149], v[226:229], v[92:95]
	v_mfma_f32_16x16x32_bf16 v[84:87], v[154:157], v[226:229], v[84:87]
	v_mfma_f32_16x16x32_bf16 v[76:79], v[146:149], v[234:237], v[76:79]
	v_mfma_f32_16x16x32_bf16 v[68:71], v[154:157], v[234:237], v[68:71]
	v_mfma_f32_16x16x32_bf16 v[120:123], v[158:161], v[192:195], v[120:123]
	v_mfma_f32_16x16x32_bf16 v[112:115], v[184:187], v[192:195], v[112:115]
	v_mfma_f32_16x16x32_bf16 v[104:107], v[158:161], v[214:217], v[104:107]
	v_mfma_f32_16x16x32_bf16 v[96:99], v[184:187], v[214:217], v[96:99]
	v_mfma_f32_16x16x32_bf16 v[88:91], v[158:161], v[222:225], v[88:91]
	v_mfma_f32_16x16x32_bf16 v[80:83], v[184:187], v[222:225], v[80:83]
	v_mfma_f32_16x16x32_bf16 v[72:75], v[158:161], v[230:233], v[72:75]
	v_mfma_f32_16x16x32_bf16 v[64:67], v[184:187], v[230:233], v[64:67]
	v_mfma_f32_16x16x32_bf16 v[120:123], v[180:183], v[196:199], v[120:123]
	v_mfma_f32_16x16x32_bf16 v[112:115], v[188:191], v[196:199], v[112:115]
	v_mfma_f32_16x16x32_bf16 v[104:107], v[180:183], v[218:221], v[104:107]
	v_mfma_f32_16x16x32_bf16 v[96:99], v[188:191], v[218:221], v[96:99]
	v_mfma_f32_16x16x32_bf16 v[88:91], v[180:183], v[226:229], v[88:91]
	v_mfma_f32_16x16x32_bf16 v[80:83], v[188:191], v[226:229], v[80:83]
	v_mfma_f32_16x16x32_bf16 v[72:75], v[180:183], v[234:237], v[72:75]
	v_mfma_f32_16x16x32_bf16 v[64:67], v[188:191], v[234:237], v[64:67]
	s_barrier
	s_add_i32 s60, s60, s41
	v_lshl_add_u64 v[162:163], s[20:21], 0, v[164:165]
	s_mov_b32 m0, s60
	ds_read_b128 v[192:195], v145 offset:16384
	ds_read_b128 v[196:199], v145 offset:17408
	ds_read_b128 v[214:217], v145 offset:18432
	ds_read_b128 v[218:221], v145 offset:19456
	ds_read_b128 v[222:225], v145 offset:20480
	ds_read_b128 v[226:229], v145 offset:21504
	ds_read_b128 v[230:233], v145 offset:22528
	ds_read_b128 v[234:237], v145 offset:23552
	global_load_lds_dwordx4 v[162:163], off
	s_add_i32 m0, s60, 0x2000
	s_add_u32 s60, s20, 0x40000
	v_lshl_add_u64 v[200:201], s[20:21], 0, v[128:129]
	s_addc_u32 s61, s21, 0
	s_add_i32 s62, s62, s41
	global_load_lds_dwordx4 v[200:201], off
	v_lshl_add_u64 v[238:239], s[60:61], 0, v[164:165]
	s_mov_b32 m0, s62
	v_lshl_add_u64 v[240:241], s[52:53], 0, v[130:131]
	global_load_lds_dwordx4 v[238:239], off
	v_lshl_add_u64 v[238:239], s[60:61], 0, v[128:129]
	s_add_i32 m0, s62, 0x2000
	s_nop 0
	global_load_lds_dwordx4 v[238:239], off
	v_lshl_add_u64 v[238:239], s[52:53], 0, v[132:133]
	s_mov_b32 m0, s43
	s_nop 0
	global_load_lds_dwordx4 v[238:239], off
	s_mov_b32 m0, s44
	s_nop 0
	global_load_lds_dwordx4 v[240:241], off
	s_waitcnt vmcnt(8)
	s_waitcnt lgkmcnt(0)
	s_barrier
; #define PG8_STAGE(bufoff, gbase, voff) do { _Pragma("unroll") for (int _i = 0; _i < 2; ++_i) \
;         __builtin_amdgcn_global_load_lds((const unsigned*)((const char*)(gbase) + (voff)[_i]), (PG8_LAS unsigned*)(lds + (bufoff) + ldsw + _i * 8192), 16, 0, 0); } while (0)
; #define PG8_LDA(dst, b, h) do { _Pragma("unroll") for (int m = 0; m < 4; ++m) _Pragma("unroll") for (int k = 0; k < 2; ++k) dst[m][k] = *(const PG8_LAS bf16x8*)(lds + PG8_SA(b, h) + aoff + m * 2048 + k * 1024); } while (0)
; #define PG8_LDB(dst, b, h) do { _Pragma("unroll") for (int n = 0; n < 2; ++n) _Pragma("unroll") for (int k = 0; k < 2; ++k) dst[n][k] = *(const PG8_LAS bf16x8*)(lds + PG8_SB(b, h) + boff + n * 2048 + k * 1024); } while (0)
; #define PG8_MMA(ai, bj, At, Bt) do { __builtin_amdgcn_s_setprio(1); _Pragma("unroll") for (int m = 0; m < 4; ++m) _Pragma("unroll") for (int n = 0; n < 2; ++n) _Pragma("unroll") for (int k = 0; k < 2; ++k) \
;         acc[ai][bj][m][n] = __builtin_amdgcn_mfma_f32_16x16x32_bf16(Bt[n][k], At[m][k], acc[ai][bj][m][n], 0, 0, 0); __builtin_amdgcn_s_setprio(0); } while (0)
; #define PG8_WAIT_V(n) asm volatile("s_waitcnt vmcnt(" #n ")" ::: "memory")
; #define PG8_WAIT_L(n) asm volatile("s_waitcnt lgkmcnt(" #n ")" ::: "memory")
; #define PG8_BAR __builtin_amdgcn_s_barrier()
; #define PG8_SCHED __builtin_amdgcn_sched_barrier(0)
; template <class Epi, class Sched, bool ALIGN_EPI = false, bool SP2 = false>
; __device__ __forceinline__ void gemm_phase(PG8_LAS unsigned char* lds, const Gemm g, const Sched& S, const Epi& E, const int tid) {
;     ...
;             PG8_WAIT_V(8); PG8_WAIT_L(0); PG8_BAR; PG8_MMA(1, 0, At, B0); PG8_MMA(1, 1, At, B1); PG8_BAR; PG8_SCHED;
;             PG8_LDB(B0, 1, 0); PG8_LDB(B1, 1, 1); PG8_SCHED; PG8_LDA(At, 1, 0); PG8_STAGE(PG8_SA(0, 1), a2 + hstep, voffA);
;             PG8_WAIT_V(8); PG8_WAIT_L(0); PG8_BAR; PG8_MMA(0, 0, At, B0); PG8_MMA(0, 1, At, B1); PG8_BAR; PG8_SCHED;
	s_waitcnt lgkmcnt(0)
	v_mfma_f32_16x16x32_bf16 v[60:63], v[138:141], v[192:195], v[60:63]
	v_mfma_f32_16x16x32_bf16 v[52:55], v[150:153], v[192:195], v[52:55]
	v_mfma_f32_16x16x32_bf16 v[44:47], v[138:141], v[214:217], v[44:47]
	v_mfma_f32_16x16x32_bf16 v[36:39], v[150:153], v[214:217], v[36:39]
	v_mfma_f32_16x16x32_bf16 v[28:31], v[138:141], v[222:225], v[28:31]
	v_mfma_f32_16x16x32_bf16 v[20:23], v[150:153], v[222:225], v[20:23]
	v_mfma_f32_16x16x32_bf16 v[12:15], v[138:141], v[230:233], v[12:15]
	v_mfma_f32_16x16x32_bf16 v[4:7], v[150:153], v[230:233], v[4:7]
	v_mfma_f32_16x16x32_bf16 v[60:63], v[146:149], v[196:199], v[60:63]
	v_mfma_f32_16x16x32_bf16 v[52:55], v[154:157], v[196:199], v[52:55]
	v_mfma_f32_16x16x32_bf16 v[44:47], v[146:149], v[218:221], v[44:47]
	v_mfma_f32_16x16x32_bf16 v[36:39], v[154:157], v[218:221], v[36:39]
	v_mfma_f32_16x16x32_bf16 v[28:31], v[146:149], v[226:229], v[28:31]
	v_mfma_f32_16x16x32_bf16 v[20:23], v[154:157], v[226:229], v[20:23]
	v_mfma_f32_16x16x32_bf16 v[12:15], v[146:149], v[234:237], v[12:15]
	v_mfma_f32_16x16x32_bf16 v[4:7], v[154:157], v[234:237], v[4:7]
	v_mfma_f32_16x16x32_bf16 v[56:59], v[158:161], v[192:195], v[56:59]
	v_mfma_f32_16x16x32_bf16 v[48:51], v[184:187], v[192:195], v[48:51]
	v_mfma_f32_16x16x32_bf16 v[40:43], v[158:161], v[214:217], v[40:43]
	v_mfma_f32_16x16x32_bf16 v[32:35], v[184:187], v[214:217], v[32:35]
	v_mfma_f32_16x16x32_bf16 v[24:27], v[158:161], v[222:225], v[24:27]
	v_mfma_f32_16x16x32_bf16 v[16:19], v[184:187], v[222:225], v[16:19]
	v_mfma_f32_16x16x32_bf16 v[8:11], v[158:161], v[230:233], v[8:11]
	v_mfma_f32_16x16x32_bf16 v[0:3], v[184:187], v[230:233], v[0:3]
	v_mfma_f32_16x16x32_bf16 v[56:59], v[180:183], v[196:199], v[56:59]
	v_mfma_f32_16x16x32_bf16 v[48:51], v[188:191], v[196:199], v[48:51]
	v_mfma_f32_16x16x32_bf16 v[40:43], v[180:183], v[218:221], v[40:43]
	v_mfma_f32_16x16x32_bf16 v[32:35], v[188:191], v[218:221], v[32:35]
	v_mfma_f32_16x16x32_bf16 v[24:27], v[180:183], v[226:229], v[24:27]
	v_mfma_f32_16x16x32_bf16 v[16:19], v[188:191], v[226:229], v[16:19]
	v_mfma_f32_16x16x32_bf16 v[8:11], v[180:183], v[234:237], v[8:11]
	v_mfma_f32_16x16x32_bf16 v[0:3], v[188:191], v[234:237], v[0:3]
	s_barrier
	s_add_i32 s60, 0, 0x18000
	s_add_i32 s61, 0, 0x1c000
	v_add_u32_e32 v154, s60, v143
	v_add_u32_e32 v166, s61, v143
	ds_read_b128 v[138:141], v154
	ds_read_b128 v[146:149], v154 offset:1024
	ds_read_b128 v[150:153], v154 offset:2048
	ds_read_b128 v[154:157], v154 offset:3072
	ds_read_b128 v[158:161], v166
	ds_read_b128 v[180:183], v166 offset:1024
	ds_read_b128 v[184:187], v166 offset:2048
	ds_read_b128 v[188:191], v166 offset:3072
	s_add_u32 s52, s52, 0x40000
	s_addc_u32 s53, s53, 0
	s_mov_b32 m0, s45
	v_lshl_add_u64 v[242:243], s[52:53], 0, v[132:133]
	ds_read_b128 v[192:195], v145 offset:32768
	ds_read_b128 v[196:199], v145 offset:33792
	ds_read_b128 v[214:217], v145 offset:34816
	ds_read_b128 v[218:221], v145 offset:35840
	ds_read_b128 v[222:225], v145 offset:36864
	ds_read_b128 v[226:229], v145 offset:37888
	ds_read_b128 v[230:233], v145 offset:38912
	ds_read_b128 v[234:237], v145 offset:39936
	global_load_lds_dwordx4 v[242:243], off
	v_lshl_add_u64 v[242:243], s[52:53], 0, v[130:131]
	s_mov_b32 m0, s48
	s_nop 0
	global_load_lds_dwordx4 v[242:243], off
	s_waitcnt vmcnt(8)
	s_waitcnt lgkmcnt(0)
	s_barrier
	s_waitcnt lgkmcnt(0)
	v_mfma_f32_16x16x32_bf16 v[124:127], v[138:141], v[192:195], v[124:127]
	v_mfma_f32_16x16x32_bf16 v[116:119], v[150:153], v[192:195], v[116:119]
	v_mfma_f32_16x16x32_bf16 v[108:111], v[138:141], v[214:217], v[108:111]
	v_mfma_f32_16x16x32_bf16 v[100:103], v[150:153], v[214:217], v[100:103]
	v_mfma_f32_16x16x32_bf16 v[92:95], v[138:141], v[222:225], v[92:95]
	v_mfma_f32_16x16x32_bf16 v[84:87], v[150:153], v[222:225], v[84:87]
	v_mfma_f32_16x16x32_bf16 v[76:79], v[138:141], v[230:233], v[76:79]
	v_mfma_f32_16x16x32_bf16 v[68:71], v[150:153], v[230:233], v[68:71]
	v_mfma_f32_16x16x32_bf16 v[124:127], v[146:149], v[196:199], v[124:127]
	v_mfma_f32_16x16x32_bf16 v[116:119], v[154:157], v[196:199], v[116:119]
	v_mfma_f32_16x16x32_bf16 v[108:111], v[146:149], v[218:221], v[108:111]
	v_mfma_f32_16x16x32_bf16 v[100:103], v[154:157], v[218:221], v[100:103]
	v_mfma_f32_16x16x32_bf16 v[92:95], v[146:149], v[226:229], v[92:95]
	v_mfma_f32_16x16x32_bf16 v[84:87], v[154:157], v[226:229], v[84:87]
	v_mfma_f32_16x16x32_bf16 v[76:79], v[146:149], v[234:237], v[76:79]
	v_mfma_f32_16x16x32_bf16 v[68:71], v[154:157], v[234:237], v[68:71]
	v_mfma_f32_16x16x32_bf16 v[120:123], v[158:161], v[192:195], v[120:123]
	v_mfma_f32_16x16x32_bf16 v[112:115], v[184:187], v[192:195], v[112:115]
	v_mfma_f32_16x16x32_bf16 v[104:107], v[158:161], v[214:217], v[104:107]
	v_mfma_f32_16x16x32_bf16 v[96:99], v[184:187], v[214:217], v[96:99]
	v_mfma_f32_16x16x32_bf16 v[88:91], v[158:161], v[222:225], v[88:91]
	v_mfma_f32_16x16x32_bf16 v[80:83], v[184:187], v[222:225], v[80:83]
	v_mfma_f32_16x16x32_bf16 v[72:75], v[158:161], v[230:233], v[72:75]
	v_mfma_f32_16x16x32_bf16 v[64:67], v[184:187], v[230:233], v[64:67]
	v_mfma_f32_16x16x32_bf16 v[120:123], v[180:183], v[196:199], v[120:123]
	v_mfma_f32_16x16x32_bf16 v[112:115], v[188:191], v[196:199], v[112:115]
	v_mfma_f32_16x16x32_bf16 v[104:107], v[180:183], v[218:221], v[104:107]
	v_mfma_f32_16x16x32_bf16 v[96:99], v[188:191], v[218:221], v[96:99]
	v_mfma_f32_16x16x32_bf16 v[88:91], v[180:183], v[226:229], v[88:91]
	v_mfma_f32_16x16x32_bf16 v[80:83], v[188:191], v[226:229], v[80:83]
	v_mfma_f32_16x16x32_bf16 v[72:75], v[180:183], v[234:237], v[72:75]
	v_mfma_f32_16x16x32_bf16 v[64:67], v[188:191], v[234:237], v[64:67]
	s_barrier
; #define PG8_STAGE(bufoff, gbase, voff) do { _Pragma("unroll") for (int _i = 0; _i < 2; ++_i) \
;         __builtin_amdgcn_global_load_lds((const unsigned*)((const char*)(gbase) + (voff)[_i]), (PG8_LAS unsigned*)(lds + (bufoff) + ldsw + _i * 8192), 16, 0, 0); } while (0)
; #define PG8_LDA(dst, b, h) do { _Pragma("unroll") for (int m = 0; m < 4; ++m) _Pragma("unroll") for (int k = 0; k < 2; ++k) dst[m][k] = *(const PG8_LAS bf16x8*)(lds + PG8_SA(b, h) + aoff + m * 2048 + k * 1024); } while (0)
; #define PG8_MMA(ai, bj, At, Bt) do { __builtin_amdgcn_s_setprio(1); _Pragma("unroll") for (int m = 0; m < 4; ++m) _Pragma("unroll") for (int n = 0; n < 2; ++n) _Pragma("unroll") for (int k = 0; k < 2; ++k) \
;         acc[ai][bj][m][n] = __builtin_amdgcn_mfma_f32_16x16x32_bf16(Bt[n][k], At[m][k], acc[ai][bj][m][n], 0, 0, 0); __builtin_amdgcn_s_setprio(0); } while (0)
; #define PG8_WAIT_V(n) asm volatile("s_waitcnt vmcnt(" #n ")" ::: "memory")
; #define PG8_WAIT_L(n) asm volatile("s_waitcnt lgkmcnt(" #n ")" ::: "memory")
; #define PG8_BAR __builtin_amdgcn_s_barrier()
; #define PG8_SCHED __builtin_amdgcn_sched_barrier(0)
; template <class Epi, class Sched, bool ALIGN_EPI = false, bool SP2 = false>
; __device__ __forceinline__ void gemm_phase(PG8_LAS unsigned char* lds, const Gemm g, const Sched& S, const Epi& E, const int tid) {
;     ...
;             PG8_LDA(At, 1, 1); PG8_STAGE(PG8_SB(1, 0), b3, voffB); PG8_STAGE(PG8_SB(1, 1), b3 + hstep, voffB); PG8_STAGE(PG8_SA(1, 0), a3, voffA);
;             PG8_WAIT_V(8); PG8_WAIT_L(0); PG8_BAR; PG8_MMA(1, 0, At, B0); PG8_MMA(1, 1, At, B1); PG8_BAR; PG8_SCHED;
	s_add_i32 s52, s60, s41
	v_lshl_add_u64 v[162:163], v[162:163], 0, s[86:87]
	s_mov_b32 m0, s52
	ds_read_b128 v[192:195], v145 offset:49152
	ds_read_b128 v[196:199], v145 offset:50176
	ds_read_b128 v[214:217], v145 offset:51200
	ds_read_b128 v[218:221], v145 offset:52224
	ds_read_b128 v[222:225], v145 offset:53248
	ds_read_b128 v[226:229], v145 offset:54272
	ds_read_b128 v[230:233], v145 offset:55296
	ds_read_b128 v[234:237], v145 offset:56320
	global_load_lds_dwordx4 v[162:163], off
	s_add_i32 m0, s52, 0x2000
	s_add_u32 s20, s20, 0x40080
	v_lshl_add_u64 v[162:163], v[200:201], 0, s[86:87]
	s_addc_u32 s21, s21, 0
	s_add_i32 s52, s61, s41
	global_load_lds_dwordx4 v[162:163], off
	v_lshl_add_u64 v[162:163], s[20:21], 0, v[164:165]
	s_mov_b32 m0, s52
	s_nop 0
	global_load_lds_dwordx4 v[162:163], off
	v_lshl_add_u64 v[162:163], s[20:21], 0, v[128:129]
	s_add_i32 m0, s52, 0x2000
	s_nop 0
	global_load_lds_dwordx4 v[162:163], off
	v_lshl_add_u64 v[162:163], v[238:239], 0, s[86:87]
	s_mov_b32 m0, s49
	s_nop 0
	global_load_lds_dwordx4 v[162:163], off
	v_lshl_add_u64 v[162:163], v[240:241], 0, s[86:87]
	s_mov_b32 m0, s50
	s_nop 0
	global_load_lds_dwordx4 v[162:163], off
	s_waitcnt vmcnt(8)
	s_waitcnt lgkmcnt(0)
	s_barrier
	s_waitcnt lgkmcnt(0)
	v_mfma_f32_16x16x32_bf16 v[60:63], v[138:141], v[192:195], v[60:63]
	v_mfma_f32_16x16x32_bf16 v[52:55], v[150:153], v[192:195], v[52:55]
	v_mfma_f32_16x16x32_bf16 v[44:47], v[138:141], v[214:217], v[44:47]
	v_mfma_f32_16x16x32_bf16 v[36:39], v[150:153], v[214:217], v[36:39]
	v_mfma_f32_16x16x32_bf16 v[28:31], v[138:141], v[222:225], v[28:31]
	v_mfma_f32_16x16x32_bf16 v[20:23], v[150:153], v[222:225], v[20:23]
	v_mfma_f32_16x16x32_bf16 v[12:15], v[138:141], v[230:233], v[12:15]
	v_mfma_f32_16x16x32_bf16 v[4:7], v[150:153], v[230:233], v[4:7]
	v_mfma_f32_16x16x32_bf16 v[60:63], v[146:149], v[196:199], v[60:63]
	v_mfma_f32_16x16x32_bf16 v[52:55], v[154:157], v[196:199], v[52:55]
	v_mfma_f32_16x16x32_bf16 v[44:47], v[146:149], v[218:221], v[44:47]
	v_mfma_f32_16x16x32_bf16 v[36:39], v[154:157], v[218:221], v[36:39]
	v_mfma_f32_16x16x32_bf16 v[28:31], v[146:149], v[226:229], v[28:31]
	v_mfma_f32_16x16x32_bf16 v[20:23], v[154:157], v[226:229], v[20:23]
	v_mfma_f32_16x16x32_bf16 v[12:15], v[146:149], v[234:237], v[12:15]
	v_mfma_f32_16x16x32_bf16 v[4:7], v[154:157], v[234:237], v[4:7]
	v_mfma_f32_16x16x32_bf16 v[56:59], v[158:161], v[192:195], v[56:59]
	v_mfma_f32_16x16x32_bf16 v[48:51], v[184:187], v[192:195], v[48:51]
	v_mfma_f32_16x16x32_bf16 v[40:43], v[158:161], v[214:217], v[40:43]
	v_mfma_f32_16x16x32_bf16 v[32:35], v[184:187], v[214:217], v[32:35]
	v_mfma_f32_16x16x32_bf16 v[24:27], v[158:161], v[222:225], v[24:27]
	v_mfma_f32_16x16x32_bf16 v[16:19], v[184:187], v[222:225], v[16:19]
	v_mfma_f32_16x16x32_bf16 v[8:11], v[158:161], v[230:233], v[8:11]
	v_mfma_f32_16x16x32_bf16 v[0:3], v[184:187], v[230:233], v[0:3]
	v_mfma_f32_16x16x32_bf16 v[56:59], v[180:183], v[196:199], v[56:59]
	v_mfma_f32_16x16x32_bf16 v[48:51], v[188:191], v[196:199], v[48:51]
	v_mfma_f32_16x16x32_bf16 v[40:43], v[180:183], v[218:221], v[40:43]
	v_mfma_f32_16x16x32_bf16 v[32:35], v[188:191], v[218:221], v[32:35]
	v_mfma_f32_16x16x32_bf16 v[24:27], v[180:183], v[226:229], v[24:27]
	v_mfma_f32_16x16x32_bf16 v[16:19], v[188:191], v[226:229], v[16:19]
	v_mfma_f32_16x16x32_bf16 v[8:11], v[180:183], v[234:237], v[8:11]
	v_mfma_f32_16x16x32_bf16 v[0:3], v[188:191], v[234:237], v[0:3]
	s_barrier
	s_add_i32 s59, s59, 2
	s_add_u32 s57, s57, 0x100
	s_addc_u32 s58, s58, 0
	s_add_u32 s18, s18, 0x100
	s_addc_u32 s19, s19, 0
	s_cmp_gt_u32 s59, 13
	s_cbranch_scc0 .LBB0_1492
	s_and_b64 vcc, exec, s[6:7]
	s_cbranch_vccz .LBB0_1495
	s_barrier
